# in-loop rstd-table prefetch: both passes' loads issued together (one memory round trip per unit instead of two)
# speedup vs baseline: 1.0040x; 1.0040x over previous
;     __device__ __forceinline__ void prefetch(const Unit& u, int idx, int tid) const {
;         if (kind == EPI_SWIGLU || kind == EPI_WIN) {
; #pragma unroll
;             for (int pass = 0; pass < 2; ++pass) {
;                 const int row = pass * 128 + (tid >> 2), qtr = tid & 3;
;                 const f32x4* p = (const f32x4*)((const float*)(ws_ + WS_SS) + (size_t)(u.pm * 256 + row) * 32 + qtr * 8);
;                 const f32x4 sv = p[0] + p[1];
;                 float s = (sv[0] + sv[1]) + (sv[2] + sv[3]); s += __shfl_xor(s, 1); s += __shfl_xor(s, 2);
;                 if (qtr == 0) tbl[(idx & 1) * 256 + row] = rsqrtf(s * (1.0f / DM) + RMS_EPS);
;                 asm volatile("" ::: "memory");
;             }
;         }
;     }
.LBB0_513:
	s_andn2_b64 vcc, exec, s[18:19]
	s_cbranch_vccnz .LBB0_507
	global_load_dwordx4 v[138:141], v[130:131], off
	global_load_dwordx4 v[142:145], v[130:131], off offset:16
	global_load_dwordx4 v[146:149], v[132:133], off
	global_load_dwordx4 v[150:153], v[132:133], off offset:16
	v_and_b32_e32 v137, 64, v228
	v_xor_b32_e32 v136, 1, v228
	v_add_u32_e32 v137, 64, v137
	v_cmp_lt_i32_e32 vcc, v136, v137
	s_waitcnt vmcnt(0)
	v_pk_add_f32 v[140:141], v[140:141], v[144:145]
	v_pk_add_f32 v[138:139], v[138:139], v[142:143]
	v_cndmask_b32_e32 v136, v228, v136, vcc
	v_add_f32_e32 v138, v138, v139
	v_add_f32_e32 v139, v140, v141
	v_lshlrev_b32_e32 v136, 2, v136
	v_add_f32_e32 v138, v138, v139
	ds_bpermute_b32 v139, v136, v138
	v_xor_b32_e32 v140, 2, v228
	v_cmp_lt_i32_e32 vcc, v140, v137
	s_waitcnt lgkmcnt(0)
	v_add_f32_e32 v138, v138, v139
	v_cndmask_b32_e32 v137, v228, v140, vcc
	v_lshlrev_b32_e32 v137, 2, v137
	ds_bpermute_b32 v139, v137, v138
	s_and_saveexec_b64 s[18:19], s[6:7]
	s_cbranch_execz .LBB0_516
	s_waitcnt lgkmcnt(0)
	v_add_f32_e32 v138, v138, v139
	v_fmamk_f32 v138, v138, 0x3a000000, v222
	v_mul_f32_e32 v139, 0x4b800000, v138
	v_cmp_gt_f32_e32 vcc, s92, v138
	s_nop 1
	v_cndmask_b32_e32 v138, v138, v139, vcc
	v_rsq_f32_e32 v138, v138
	s_nop 0
	v_mul_f32_e32 v139, 0x45800000, v138
	v_cndmask_b32_e32 v138, v138, v139, vcc
	ds_write_b32 v134, v138
.LBB0_516:
	s_or_b64 exec, exec, s[18:19]
	s_waitcnt lgkmcnt(0)
	v_pk_add_f32 v[148:149], v[148:149], v[152:153]
	v_pk_add_f32 v[146:147], v[146:147], v[150:151]
	s_nop 0
	v_add_f32_e32 v146, v146, v147
	v_add_f32_e32 v147, v148, v149
	v_add_f32_e32 v146, v146, v147
	ds_bpermute_b32 v136, v136, v146
	s_waitcnt lgkmcnt(0)
	v_add_f32_e32 v136, v146, v136
	ds_bpermute_b32 v137, v137, v136
	s_and_saveexec_b64 s[18:19], s[6:7]
	s_cbranch_execz .LBB0_506
	s_waitcnt lgkmcnt(0)
	v_add_f32_e32 v136, v136, v137
	v_fmamk_f32 v136, v136, 0x3a000000, v222
	v_mul_f32_e32 v137, 0x4b800000, v136
	v_cmp_gt_f32_e32 vcc, s92, v136
	s_nop 1
	v_cndmask_b32_e32 v136, v136, v137, vcc
	v_rsq_f32_e32 v136, v136
	s_nop 0
	v_mul_f32_e32 v137, 0x45800000, v136
	v_cndmask_b32_e32 v136, v136, v137, vcc
	ds_write_b32 v135, v136
	s_branch .LBB0_506
